# prologue de-serialisation: MLA per-call prologue issues the five tile-1 K/V loads with the tile-0 loads (plus the same change in the diff prologue)
# baseline (speedup 1.0000x reference)
; __device__ __forceinline__ int v_st(int k, int c) { const int kk = (k & ~0xC) | ((k & 4) << 1) | ((k & 8) >> 1); return ((kk >> 3) * 4 + (c >> 5)) * 512 + ((kk & 7) * 32 + (c & 31)) * 2; }
; __device__ __forceinline__ int v_rd_base(int lane) { return ((lane & 3) << 3) | (((lane >> 2) & 3) << 6) | (((lane >> 4) & 1) << 5) | (((lane >> 5) & 1) << 8); }
; template <int DQK, int DK1, int LDQ, int LDK, int LDKR, int LDV, int NQL, int SDEPTH>
; __device__ __forceinline__ void attn_core(const AttnArgs& a, char* lds, f32x16 (&o)[4]) {
;     ...
;     char* QL = lds + 2 * SHM_V + 2 * SHM_K + 2048 + tid * 16;
;     { const bf16_t* Qw = a.Q + (long)(wid * 32 + r32) * LDQ + hi * 8;
; #pragma unroll
;       for (int d0 = 0; d0 < NQR; ++d0) qr[d0] = *(const bf16x8*)(Qw + d0 * 16);
; #pragma unroll
;       for (int d0 = NQR; d0 < ND0; ++d0) *(bf16x8*)(QL + (d0 - NQR) * 8192) = *(const bf16x8*)(Qw + d0 * 16); }
;     const int sr = tid >> 4, sc = (tid & 15) * 8, vst0 = v_st(sr, sc), vst1 = v_st(32 + sr, sc);
;     const int vb0 = (int)(uintptr_t)V_lds + v_rd_base(lane);
;     const bf16_t* kptr[KCH]; int kld[KCH], kwo[KCH];
; #pragma unroll
;     for (int c = 0; c < KCH; ++c) { const int idx = tid + c * 512, kr_ = idx / CPR, kc = (idx % CPR) * 8;
;         if (kc < DK1) { kptr[c] = a.Kn + (long)kr_ * LDK + kc; kld[c] = LDK; } else { kptr[c] = a.Kr + (long)kr_ * LDKR + (kc - DK1); kld[c] = LDKR; }
;         kwo[c] = kr_ * KP + ((kc * 2) ^ ((kr_ & 7) << 4)); }
;     struct { bf16x8 vs0, vs1, ks[KCH]; } sr_[SDEPTH];
;     int kb[4];
; #pragma unroll
;     for (int m = 0; m < 4; ++m) kb[m] = r32 * KP + ((m * 32 + hi * 16) ^ ((r32 & 7) << 4));
.LBB0_206:
	s_and_b32 s24, s14, 7
	s_mul_i32 s15, s23, 0xc00
	s_mul_hi_i32 s14, s23, 0xc00
	s_add_u32 s15, s4, s15
	s_addc_u32 s14, s5, s14
	s_mul_i32 s20, s24, 0x180
	s_add_u32 s20, s15, s20
	v_mov_b32_e32 v9, v159
	s_addc_u32 s21, s14, 0
	s_lshl_b32 s14, s24, 9
	v_ashrrev_i32_e32 v0, 1, v9
	v_bfe_u32 v2, v9, 5, 1
	v_bfi_b32 v3, s33, v0, v9
	v_mov_b64_e32 v[0:1], s[20:21]
	v_lshlrev_b32_e32 v8, 4, v9
	v_mad_i64_i32 v[0:1], s[20:21], v3, s77, v[0:1]
	v_lshlrev_b32_e32 v96, 4, v2
	v_lshl_add_u64 v[4:5], v[0:1], 0, v[96:97]
	v_add_u32_e32 v0, 0, v8
	global_load_dwordx4 v[126:129], v[4:5], off
	global_load_dwordx4 v[122:125], v[4:5], off offset:32
	global_load_dwordx4 v[118:121], v[4:5], off offset:64
	global_load_dwordx4 v[114:117], v[4:5], off offset:96
	global_load_dwordx4 v[110:113], v[4:5], off offset:128
	global_load_dwordx4 v[106:109], v[4:5], off offset:160
	global_load_dwordx4 v[102:105], v[4:5], off offset:192
	global_load_dwordx4 v[98:101], v[4:5], off offset:224
	v_add_u32_e32 v181, 0x14800, v0
	global_load_dwordx4 v[64:67], v[4:5], off offset:256
	global_load_dwordx4 v[68:71], v[4:5], off offset:288
	global_load_dwordx4 v[72:75], v[4:5], off offset:320
	global_load_dwordx4 v[76:79], v[4:5], off offset:352
	s_add_u32 s14, s6, s14
	s_addc_u32 s15, s7, 0
	v_mul_hi_i32 v0, v9, s86
	v_lshrrev_b32_e32 v1, 31, v0
	v_ashrrev_i32_e32 v0, 2, v0
	v_add_u32_e32 v0, v0, v1
	v_mul_lo_u32 v1, v0, 24
	v_sub_u32_e32 v10, v9, v1
	v_lshlrev_b32_e32 v2, 3, v10
	v_cmp_lt_i32_e32 vcc, 15, v10
	v_ashrrev_i32_e32 v1, 31, v0
	s_and_saveexec_b64 s[20:21], vcc
	s_xor_b64 s[20:21], exec, s[20:21]
	v_lshlrev_b64 v[4:5], 7, v[0:1]
	v_lshl_add_u64 v[4:5], s[18:19], 0, v[4:5]
	v_mov_b32_e32 v3, v97
	s_movk_i32 s38, 0xff00
	v_lshl_add_u64 v[2:3], v[2:3], 1, v[4:5]
	s_mov_b32 s39, -1
	v_lshl_add_u64 v[162:163], v[2:3], 0, s[38:39]
	s_or_saveexec_b64 s[20:21], s[20:21]
	v_mov_b64_e32 v[164:165], 64
	s_xor_b64 exec, exec, s[20:21]
	v_lshlrev_b64 v[4:5], 12, v[0:1]
	v_lshl_add_u64 v[4:5], s[14:15], 0, v[4:5]
	v_ashrrev_i32_e32 v3, 31, v2
	v_lshl_add_u64 v[162:163], v[2:3], 1, v[4:5]
	v_mov_b64_e32 v[164:165], 0x800
	s_or_b64 exec, exec, s[20:21]
	v_add_u32_e32 v1, 0x200, v9
	v_mul_hi_i32 v2, v1, s86
	v_lshrrev_b32_e32 v3, 31, v2
	v_ashrrev_i32_e32 v2, 2, v2
	v_add_u32_e32 v4, v2, v3
	v_mul_lo_u32 v2, v4, 24
	v_sub_u32_e32 v11, v1, v2
	v_lshlrev_b32_e32 v2, 3, v11
	v_cmp_lt_i32_e32 vcc, 15, v11
	v_ashrrev_i32_e32 v5, 31, v4
	s_and_saveexec_b64 s[20:21], vcc
	s_xor_b64 s[20:21], exec, s[20:21]
	v_lshlrev_b64 v[6:7], 7, v[4:5]
	v_lshl_add_u64 v[6:7], s[18:19], 0, v[6:7]
	v_mov_b32_e32 v3, v97
	s_movk_i32 s38, 0xff00
	v_lshl_add_u64 v[2:3], v[2:3], 1, v[6:7]
	s_mov_b32 s39, -1
	v_lshl_add_u64 v[166:167], v[2:3], 0, s[38:39]
	s_or_saveexec_b64 s[20:21], s[20:21]
	v_mov_b64_e32 v[168:169], 64
	s_xor_b64 exec, exec, s[20:21]
	v_lshlrev_b64 v[6:7], 12, v[4:5]
	v_lshl_add_u64 v[6:7], s[14:15], 0, v[6:7]
	v_ashrrev_i32_e32 v3, 31, v2
	v_lshl_add_u64 v[166:167], v[2:3], 1, v[6:7]
	v_mov_b64_e32 v[168:169], 0x800
	s_or_b64 exec, exec, s[20:21]
	v_add_u32_e32 v1, 0x400, v9
	v_mul_hi_i32 v2, v1, s86
	v_lshrrev_b32_e32 v3, 31, v2
	v_ashrrev_i32_e32 v2, 2, v2
	v_add_u32_e32 v2, v2, v3
	v_mul_lo_u32 v3, v2, 24
	v_sub_u32_e32 v1, v1, v3
	v_lshlrev_b32_e32 v6, 3, v1
	v_cmp_lt_i32_e32 vcc, 15, v1
	v_ashrrev_i32_e32 v3, 31, v2
	s_and_saveexec_b64 s[20:21], vcc
	s_xor_b64 s[20:21], exec, s[20:21]
	v_lshlrev_b64 v[12:13], 7, v[2:3]
	v_lshl_add_u64 v[12:13], s[18:19], 0, v[12:13]
	v_mov_b32_e32 v7, v97
	s_movk_i32 s38, 0xff00
	v_lshl_add_u64 v[6:7], v[6:7], 1, v[12:13]
	s_mov_b32 s39, -1
	v_lshl_add_u64 v[170:171], v[6:7], 0, s[38:39]
	s_or_saveexec_b64 s[20:21], s[20:21]
	v_mov_b64_e32 v[172:173], 64
	s_xor_b64 exec, exec, s[20:21]
	v_lshlrev_b64 v[12:13], 12, v[2:3]
	v_lshl_add_u64 v[12:13], s[14:15], 0, v[12:13]
	v_ashrrev_i32_e32 v7, 31, v6
	v_lshl_add_u64 v[170:171], v[6:7], 1, v[12:13]
	v_mov_b64_e32 v[172:173], 0x800
	s_or_b64 exec, exec, s[20:21]
	v_mul_lo_u32 v3, v4, s84
	v_bitop3_b32 v4, v4, v11, 7 bitop3:0x6c
	v_ashrrev_i32_e32 v174, 4, v9
	v_lshl_add_u32 v20, v4, 4, v3
	v_and_b32_e32 v4, 0xfffff0, v174
	v_lshlrev_b32_e32 v5, 1, v174
	v_and_or_b32 v4, v5, 8, v4
	v_lshrrev_b32_e32 v5, 1, v174
	v_and_b32_e32 v6, 3, v174
	v_mul_lo_u32 v3, v0, s84
	v_bitop3_b32 v0, v0, v10, 7 bitop3:0x6c
	v_and_or_b32 v5, v5, 4, v6
	v_add_u32_e32 v6, 32, v174
	v_lshl_add_u32 v21, v0, 4, v3
	v_and_b32_e32 v0, 0x3fffffc0, v9
	s_add_i32 s20, 0, 0x14000
	v_and_b32_e32 v7, 0xfffff0, v6
	v_lshlrev_b32_e32 v6, 1, v6
	v_and_b32_e32 v52, 63, v9
	v_lshl_add_u32 v161, v0, 2, s20
	v_lshlrev_b32_e32 v0, 3, v9
	v_and_or_b32 v6, v6, 8, v7
	v_and_b32_e32 v3, 0x78, v0
	v_lshrrev_b32_e32 v4, 1, v4
	v_bfe_u32 v0, v0, 5, 2
	v_lshrrev_b32_e32 v6, 1, v6
	v_lshlrev_b32_e32 v7, 4, v52
	v_and_b32_e32 v51, 31, v9
	v_or_b32_e32 v4, v4, v0
	v_or_b32_e32 v0, v6, v0
	v_lshlrev_b32_e32 v6, 3, v52
	v_and_b32_e32 v7, 0xc0, v7
	v_lshlrev_b32_e32 v9, 1, v52
	v_and_or_b32 v7, v6, 24, v7
	v_and_b32_e32 v9, 32, v9
	v_and_b32_e32 v6, 0x100, v6
	v_or3_b32 v53, v7, v9, v6
	v_mul_lo_u32 v6, v2, s84
	v_bitop3_b32 v1, v2, v1, 7 bitop3:0x6c
	s_lshl_b32 s20, s68, 6
	v_lshlrev_b32_e32 v5, 6, v5
	v_lshlrev_b32_e32 v0, 9, v0
	v_lshl_add_u32 v22, v1, 4, v6
	v_and_b32_e32 v1, 48, v8
	s_sub_i32 s20, s28, s20
	v_or3_b32 v23, v0, v5, v1
	v_mul_u32_u24_e32 v0, 0x180, v51
	v_and_b32_e32 v2, 0x70, v8
	v_or_b32_e32 v6, 32, v96
	s_and_b64 s[12:13], s[12:13], exec
	v_bitop3_b32 v50, v6, v0, v2 bitop3:0xde
	v_or_b32_e32 v6, 64, v96
	s_cselect_b32 s12, s25, s20
	v_ashrrev_i32_e32 v175, 31, v174
	v_lshlrev_b32_e32 v4, 9, v4
	v_bitop3_b32 v62, v6, v0, v2 bitop3:0xde
; #define SLOAD(i, j) do { const long rb_ = KROW(j); sr_[i].vs0 = *(const bf16x8*)(a.V + (rb_ + sr) * LDV + sc); sr_[i].vs1 = *(const bf16x8*)(a.V + (rb_ + 32 + sr) * LDV + sc); \
;     _Pragma("unroll") for (int c_ = 0; c_ < KCH; ++c_) sr_[i].ks[c_] = *(const bf16x8*)(kptr[c_] + rb_ * kld[c_]); } while (0)
; #define SWRITE(b, i) do { *(bf16x8*)(V_lds + (b) * SHM_V + vst0) = sr_[i].vs0; *(bf16x8*)(V_lds + (b) * SHM_V + vst1) = sr_[i].vs1; \
;     _Pragma("unroll") for (int c_ = 0; c_ < KCH; ++c_) *(bf16x8*)(K_lds + (b) * SHM_K + kwo[c_]) = sr_[i].ks[c_]; } while (0)
; template <int DQK, int DK1, int LDQ, int LDK, int LDKR, int LDV, int NQL, int SDEPTH>
; __device__ __forceinline__ void attn_core(const AttnArgs& a, char* lds, f32x16 (&o)[4]) {
;     ...
;     f32x16 pA0, pA1, pB0, pB1; float mnA, mnB, alA, alB; bf16x8 pa0, pa1, pa2, pa3; const int NT = a.NT;
;     constexpr int SE = 0, SO = SDEPTH - 1;
;     SLOAD(SE, 0); asm volatile("s_waitcnt vmcnt(0)" ::: "memory"); SWRITE(0, SE); __syncthreads();
;     QKT(pA0, pA1, K_lds); partialSM(pA0, pA1, m_reg, mnA, alA, a.C, a.thr);
;     SLOAD(SO, 1); if (SDEPTH == 2 && 2 < NT) SLOAD(SE, 2);
	v_or_b32_e32 v6, 0x60, v96
	s_ashr_i32 s13, s12, 31
	v_lshl_add_u64 v[176:177], v[174:175], 0, 32
	v_bitop3_b32 v24, v96, v0, v2 bitop3:0xde
	v_bitop3_b32 v63, v6, v0, v2 bitop3:0xde
	v_or3_b32 v25, v4, v5, v1
	v_lshl_add_u64 v[0:1], v[174:175], 0, s[12:13]
	v_lshl_add_u64 v[4:5], v[176:177], 0, s[12:13]
	v_lshlrev_b64 v[0:1], 12, v[0:1]
	v_lshlrev_b64 v[4:5], 12, v[4:5]
	v_lshl_add_u64 v[0:1], s[14:15], 0, v[0:1]
	v_lshlrev_b32_e32 v48, 1, v3
	v_mov_b32_e32 v49, v97
	v_lshl_add_u64 v[4:5], s[14:15], 0, v[4:5]
	v_mad_i64_i32 v[8:9], s[20:21], v164, s12, 0
	v_mad_i64_i32 v[12:13], s[20:21], v168, s12, 0
	v_mad_i64_i32 v[16:17], s[20:21], v172, s12, 0
	v_lshl_add_u64 v[0:1], v[0:1], 0, v[48:49]
	v_lshl_add_u64 v[4:5], v[4:5], 0, v[48:49]
	v_lshl_add_u64 v[8:9], v[8:9], 1, v[162:163]
	v_lshl_add_u64 v[12:13], v[12:13], 1, v[166:167]
	v_lshl_add_u64 v[16:17], v[16:17], 1, v[170:171]
	global_load_dwordx4 v[0:3], v[0:1], off offset:256
	v_add_u32_e32 v186, 0, v25
	global_load_dwordx4 v[4:7], v[4:5], off offset:256
	v_add_u32_e32 v188, 0, v23
	global_load_dwordx4 v[8:11], v[8:9], off
	v_add_u32_e32 v194, 0, v21
	global_load_dwordx4 v[12:15], v[12:13], off
	v_add_u32_e32 v196, 0, v20
	global_load_dwordx4 v[16:19], v[16:17], off
	s_or_b32 s100, s12, 64
	s_ashr_i32 s101, s100, 31
	v_lshl_add_u64 v[228:229], v[174:175], 0, s[100:101]
	v_lshl_add_u64 v[232:233], v[176:177], 0, s[100:101]
	v_lshlrev_b64 v[228:229], 12, v[228:229]
	v_lshlrev_b64 v[232:233], 12, v[232:233]
	v_lshl_add_u64 v[228:229], s[14:15], 0, v[228:229]
	v_lshl_add_u64 v[232:233], s[14:15], 0, v[232:233]
	v_mad_i64_i32 v[236:237], vcc, v164, s100, 0
	v_mad_i64_i32 v[240:241], vcc, v168, s100, 0
	v_mad_i64_i32 v[244:245], vcc, v172, s100, 0
	v_lshl_add_u64 v[228:229], v[228:229], 0, v[48:49]
	v_lshl_add_u64 v[232:233], v[232:233], 0, v[48:49]
	v_lshl_add_u64 v[236:237], v[236:237], 1, v[162:163]
	v_lshl_add_u64 v[240:241], v[240:241], 1, v[166:167]
	v_lshl_add_u64 v[244:245], v[244:245], 1, v[170:171]
	global_load_dwordx4 v[228:231], v[228:229], off offset:256
	s_nop 0
	global_load_dwordx4 v[232:235], v[232:233], off offset:256
	s_nop 0
	global_load_dwordx4 v[236:239], v[236:237], off
	s_nop 0
	global_load_dwordx4 v[240:243], v[240:241], off
	s_nop 0
	global_load_dwordx4 v[244:247], v[244:245], off
	v_add_u32_e32 v198, 0, v22
	v_add_u32_e32 v184, 0, v24
	s_waitcnt vmcnt(0)
	v_add_u32_e32 v192, 0, v50
	v_add_u32_e32 v190, 0, v62
	v_add_u32_e32 v173, 0, v63
	s_mov_b32 s37, s36
	s_mov_b32 s38, s36
	s_mov_b32 s39, s36
	s_mov_b32 s40, s36
	s_mov_b32 s41, s36
	s_mov_b32 s42, s36
	s_mov_b32 s43, s36
	s_mov_b32 s44, s36
	s_mov_b32 s45, s36
	s_mov_b32 s46, s36
	s_mov_b32 s47, s36
	s_mov_b32 s48, s36
	s_mov_b32 s49, s36
	s_mov_b32 s50, s36
	s_mov_b32 s51, s36
	v_lshl_add_u32 v165, v51, 2, v161
	v_lshl_add_u64 v[178:179], s[14:15], 0, v[48:49]
	s_mov_b32 s69, 2
	v_add_u32_e32 v216, 0xe000, v184
	v_add_u32_e32 v208, 0xe000, v192
	v_add_u32_e32 v206, 0xe000, v190
	v_add_u32_e32 v202, 0xe000, v173
	v_mov_b32_e32 v182, 0
	s_waitcnt vmcnt(0)
	ds_write_b128 v181, v[64:67]
	ds_write_b128 v181, v[68:71] offset:8192
	ds_write_b128 v181, v[72:75] offset:16384
	ds_write_b128 v181, v[76:79] offset:24576
	ds_write_b128 v186, v[0:3]
	ds_write_b128 v188, v[4:7]
	ds_write_b128 v194, v[8:11] offset:32768
	ds_write_b128 v196, v[12:15] offset:32768
	v_mov_b64_e32 v[0:1], s[36:37]
	ds_write_b128 v198, v[16:19] offset:32768
	s_waitcnt lgkmcnt(0)
	s_barrier
	ds_read_b128 v[16:19], v184 offset:32768
	ds_read_b128 v[20:23], v184 offset:45056
	s_waitcnt lgkmcnt(1)
	v_mfma_f32_32x32x16_bf16 v[32:47], v[16:19], v[126:129], 0
	ds_read_b128 v[54:57], v192 offset:32768
	ds_read_b128 v[58:61], v192 offset:45056
	v_mov_b64_e32 v[14:15], s[50:51]
	v_mov_b64_e32 v[2:3], s[38:39]
	v_mov_b64_e32 v[4:5], s[40:41]
	v_mov_b64_e32 v[6:7], s[42:43]
	v_mov_b64_e32 v[8:9], s[44:45]
	v_mov_b64_e32 v[10:11], s[46:47]
	s_waitcnt lgkmcnt(2)
	v_mfma_f32_32x32x16_bf16 v[16:31], v[20:23], v[126:129], 0
	v_mov_b64_e32 v[12:13], s[48:49]
	s_movk_i32 s37, 0x80
	s_waitcnt lgkmcnt(1)
	v_mfma_f32_32x32x16_bf16 v[32:47], v[54:57], v[122:125], v[32:47]
	s_waitcnt lgkmcnt(0)
	v_mfma_f32_32x32x16_bf16 v[16:31], v[58:61], v[122:125], v[16:31]
	ds_read_b128 v[54:57], v190 offset:32768
	ds_read_b128 v[58:61], v190 offset:45056
	s_waitcnt lgkmcnt(1)
	v_mfma_f32_32x32x16_bf16 v[32:47], v[54:57], v[118:121], v[32:47]
	s_waitcnt lgkmcnt(0)
	v_mfma_f32_32x32x16_bf16 v[16:31], v[58:61], v[118:121], v[16:31]
	ds_read_b128 v[54:57], v173 offset:32768
	ds_read_b128 v[58:61], v173 offset:45056
	s_waitcnt lgkmcnt(1)
	v_mfma_f32_32x32x16_bf16 v[32:47], v[54:57], v[114:117], v[32:47]
	s_waitcnt lgkmcnt(0)
	v_mfma_f32_32x32x16_bf16 v[16:31], v[58:61], v[114:117], v[16:31]
	ds_read_b128 v[54:57], v184 offset:32896
	ds_read_b128 v[58:61], v184 offset:45184
	s_waitcnt lgkmcnt(1)
	v_mfma_f32_32x32x16_bf16 v[32:47], v[54:57], v[110:113], v[32:47]
	s_waitcnt lgkmcnt(0)
	v_mfma_f32_32x32x16_bf16 v[16:31], v[58:61], v[110:113], v[16:31]
	ds_read_b128 v[54:57], v192 offset:32896
	ds_read_b128 v[58:61], v192 offset:45184
	s_waitcnt lgkmcnt(1)
	v_mfma_f32_32x32x16_bf16 v[32:47], v[54:57], v[106:109], v[32:47]
	s_waitcnt lgkmcnt(0)
	v_mfma_f32_32x32x16_bf16 v[16:31], v[58:61], v[106:109], v[16:31]
	ds_read_b128 v[54:57], v190 offset:32896
	ds_read_b128 v[58:61], v190 offset:45184
	s_waitcnt lgkmcnt(1)
	v_mfma_f32_32x32x16_bf16 v[32:47], v[54:57], v[102:105], v[32:47]
	s_waitcnt lgkmcnt(0)
; #define SLOAD(i, j) do { const long rb_ = KROW(j); sr_[i].vs0 = *(const bf16x8*)(a.V + (rb_ + sr) * LDV + sc); sr_[i].vs1 = *(const bf16x8*)(a.V + (rb_ + 32 + sr) * LDV + sc); \
;     _Pragma("unroll") for (int c_ = 0; c_ < KCH; ++c_) sr_[i].ks[c_] = *(const bf16x8*)(kptr[c_] + rb_ * kld[c_]); } while (0)
; #define SWRITE(b, i) do { *(bf16x8*)(V_lds + (b) * SHM_V + vst0) = sr_[i].vs0; *(bf16x8*)(V_lds + (b) * SHM_V + vst1) = sr_[i].vs1; \
;     _Pragma("unroll") for (int c_ = 0; c_ < KCH; ++c_) *(bf16x8*)(K_lds + (b) * SHM_K + kwo[c_]) = sr_[i].ks[c_]; } while (0)
; __device__ __forceinline__ void partialSM(f32x16& p0, f32x16& p1, float& m_reg, float& mn, float& alpha, const float C, const float thr) {
;     float pmax = p0[0];
; #pragma unroll
;     for (int r = 1; r < 16; ++r) pmax = fmaxf(pmax, p0[r]);
; #pragma unroll
;     for (int r = 0; r < 16; ++r) pmax = fmaxf(pmax, p1[r]);
;     { auto rr = __builtin_amdgcn_permlane32_swap(__float_as_uint(pmax), __float_as_uint(pmax), false, false);
;       pmax = fmaxf(__uint_as_float(rr[0]), __uint_as_float(rr[1])); }
;     if (__builtin_expect(__all(pmax - m_reg <= thr), 1)) { mn = m_reg; alpha = 1.f; }
;     else { mn = fmaxf(m_reg, pmax); alpha = __builtin_amdgcn_exp2f((m_reg - mn) * C); m_reg = mn; }
;     const float mnC = -mn * C;
; #pragma unroll
;     for (int r = 0; r < 16; ++r) p0[r] = fmaf(p0[r], C, mnC);
; #pragma unroll
;     for (int r = 0; r < 16; ++r) p1[r] = fmaf(p1[r], C, mnC);
; #pragma unroll
;     for (int r = 0; r < 16; ++r) p0[r] = __builtin_amdgcn_exp2f(p0[r]);
; }
; template <int DQK, int DK1, int LDQ, int LDK, int LDKR, int LDV, int NQL, int SDEPTH>
; __device__ __forceinline__ void attn_core(const AttnArgs& a, char* lds, f32x16 (&o)[4]) {
;     ...
;     f32x16 pA0, pA1, pB0, pB1; float mnA, mnB, alA, alB; bf16x8 pa0, pa1, pa2, pa3; const int NT = a.NT;
;     constexpr int SE = 0, SO = SDEPTH - 1;
;     SLOAD(SE, 0); asm volatile("s_waitcnt vmcnt(0)" ::: "memory"); SWRITE(0, SE); __syncthreads();
;     QKT(pA0, pA1, K_lds); partialSM(pA0, pA1, m_reg, mnA, alA, a.C, a.thr);
;     SLOAD(SO, 1); if (SDEPTH == 2 && 2 < NT) SLOAD(SE, 2);
;     SWRITE(1, SO); __syncthreads();
	v_mfma_f32_32x32x16_bf16 v[16:31], v[58:61], v[102:105], v[16:31]
	ds_read_b128 v[54:57], v173 offset:32896
	ds_read_b128 v[58:61], v173 offset:45184
	s_waitcnt lgkmcnt(1)
	v_mfma_f32_32x32x16_bf16 v[32:47], v[54:57], v[98:101], v[32:47]
	s_waitcnt lgkmcnt(0)
	v_mfma_f32_32x32x16_bf16 v[16:31], v[58:61], v[98:101], v[16:31]
	ds_read_b128 v[54:57], v184 offset:33024
	ds_read_b128 v[58:61], v184 offset:45312
	ds_read_b128 v[62:65], v181
	s_waitcnt lgkmcnt(0)
	v_mfma_f32_32x32x16_bf16 v[32:47], v[54:57], v[62:65], v[32:47]
	v_mfma_f32_32x32x16_bf16 v[16:31], v[58:61], v[62:65], v[16:31]
	ds_read_b128 v[54:57], v192 offset:33024
	ds_read_b128 v[58:61], v192 offset:45312
	ds_read_b128 v[62:65], v181 offset:8192
	s_waitcnt lgkmcnt(0)
	v_mfma_f32_32x32x16_bf16 v[32:47], v[54:57], v[62:65], v[32:47]
	v_mfma_f32_32x32x16_bf16 v[16:31], v[58:61], v[62:65], v[16:31]
	ds_read_b128 v[54:57], v190 offset:33024
	ds_read_b128 v[58:61], v190 offset:45312
	ds_read_b128 v[62:65], v181 offset:16384
	s_waitcnt lgkmcnt(0)
	v_mfma_f32_32x32x16_bf16 v[32:47], v[54:57], v[62:65], v[32:47]
	v_mfma_f32_32x32x16_bf16 v[16:31], v[58:61], v[62:65], v[16:31]
	ds_read_b128 v[54:57], v173 offset:33024
	ds_read_b128 v[58:61], v173 offset:45312
	ds_read_b128 v[62:65], v181 offset:24576
	s_waitcnt lgkmcnt(0)
	v_mfma_f32_32x32x16_bf16 v[32:47], v[54:57], v[62:65], v[32:47]
	v_mfma_f32_32x32x16_bf16 v[16:31], v[58:61], v[62:65], v[16:31]
	s_nop 10
	v_max_f32_e32 v50, v33, v33
	v_max_f32_e32 v54, v32, v32
	v_max_f32_e32 v50, v54, v50
	v_max3_f32 v50, v50, v34, v35
	v_max3_f32 v50, v50, v36, v37
	v_max3_f32 v50, v50, v38, v39
	v_max3_f32 v50, v50, v40, v41
	v_max3_f32 v50, v50, v42, v43
	v_max3_f32 v50, v50, v44, v45
	v_max3_f32 v50, v50, v46, v47
	v_max3_f32 v50, v50, v16, v17
	v_max3_f32 v50, v50, v18, v19
	v_max3_f32 v50, v50, v20, v21
	v_max3_f32 v50, v50, v22, v23
	v_max3_f32 v50, v50, v24, v25
	v_max3_f32 v50, v50, v26, v27
	v_max3_f32 v50, v50, v28, v29
	v_max3_f32 v50, v50, v30, v31
	v_mov_b32_e32 v54, v50
	s_nop 1
	v_permlane32_swap_b32_e32 v50, v54
	v_max_f32_e32 v54, v54, v54
	v_max_f32_e32 v50, v50, v50
	v_max_f32_e32 v50, v50, v54
	v_add_f32_e32 v54, 0x7149f2ca, v50
	v_cmp_ge_f32_e32 vcc, s72, v54
	s_cmp_eq_u64 vcc, exec
	s_cselect_b64 vcc, -1, 0
	v_max_f32_e32 v50, 0xf149f2ca, v50
	v_cndmask_b32_e32 v204, v50, v193, vcc
	v_sub_f32_e32 v54, 0xf149f2ca, v50
	v_mul_f32_e32 v50, 0xbdd53b94, v204
	s_or_b32 s12, s12, 64
	v_fmamk_f32 v32, v32, 0x3dd53b94, v50
	v_fmamk_f32 v33, v33, 0x3dd53b94, v50
	s_ashr_i32 s13, s12, 31
	v_fmamk_f32 v36, v36, 0x3dd53b94, v50
	v_fmamk_f32 v37, v37, 0x3dd53b94, v50
	v_exp_f32_e32 v219, v32
	v_exp_f32_e32 v221, v33
	v_exp_f32_e32 v156, v36
	v_exp_f32_e32 v218, v37
	v_fmamk_f32 v34, v34, 0x3dd53b94, v50
	v_fmamk_f32 v35, v35, 0x3dd53b94, v50
	v_fmamk_f32 v40, v40, 0x3dd53b94, v50
	v_fmamk_f32 v41, v41, 0x3dd53b94, v50
	v_fmamk_f32 v38, v38, 0x3dd53b94, v50
	v_fmamk_f32 v39, v39, 0x3dd53b94, v50
	v_fmamk_f32 v44, v44, 0x3dd53b94, v50
	v_fmamk_f32 v45, v45, 0x3dd53b94, v50
	v_exp_f32_e32 v157, v34
	v_exp_f32_e32 v220, v35
	v_exp_f32_e32 v151, v40
	v_exp_f32_e32 v153, v41
	v_fmamk_f32 v42, v42, 0x3dd53b94, v50
	v_fmamk_f32 v43, v43, 0x3dd53b94, v50
	v_exp_f32_e32 v154, v38
	v_exp_f32_e32 v155, v39
	v_exp_f32_e32 v147, v44
	v_exp_f32_e32 v149, v45
	v_mul_f32_e32 v58, 0x3dd53b94, v54
	v_fmamk_f32 v46, v46, 0x3dd53b94, v50
	v_fmamk_f32 v47, v47, 0x3dd53b94, v50
	v_exp_f32_e32 v150, v42
	v_exp_f32_e32 v152, v43
	v_exp_f32_e32 v146, v46
	v_exp_f32_e32 v148, v47
	v_exp_f32_e32 v58, v58
	s_cmp_lg_u32 0, -1
	s_cselect_b32 s20, 0, 0
	v_add_u32_e32 v200, s20, v53
	s_addk_i32 s20, 0x4000
	s_waitcnt vmcnt(4)
	ds_write_b128 v186, v[228:231] offset:16384
	s_waitcnt vmcnt(3)
	ds_write_b128 v188, v[232:235] offset:16384
	s_waitcnt vmcnt(2)
	ds_write_b128 v194, v[236:239] offset:57344
	s_waitcnt vmcnt(1)
	ds_write_b128 v196, v[240:243] offset:57344
	s_waitcnt vmcnt(0)
	ds_write_b128 v198, v[244:247] offset:57344
	v_cndmask_b32_e64 v217, v58, 1.0, vcc
	v_pk_fma_f32 v[136:137], v[30:31], s[60:61], v[50:51] op_sel_hi:[1,0,0]
	v_pk_fma_f32 v[138:139], v[28:29], s[60:61], v[50:51] op_sel_hi:[1,0,0]
	v_pk_fma_f32 v[144:145], v[26:27], s[60:61], v[50:51] op_sel_hi:[1,0,0]
	v_pk_fma_f32 v[130:131], v[24:25], s[60:61], v[50:51] op_sel_hi:[1,0,0]
	v_pk_fma_f32 v[132:133], v[22:23], s[60:61], v[50:51] op_sel_hi:[1,0,0]
	v_pk_fma_f32 v[134:135], v[20:21], s[60:61], v[50:51] op_sel_hi:[1,0,0]
	v_pk_fma_f32 v[140:141], v[18:19], s[60:61], v[50:51] op_sel_hi:[1,0,0]
	v_pk_fma_f32 v[142:143], v[16:17], s[60:61], v[50:51] op_sel_hi:[1,0,0]
	v_cmp_gt_u32_e64 s[12:13], 32, v52
	v_add_u32_e32 v169, s20, v53
	v_mov_b64_e32 v[30:31], v[14:15]
	v_mov_b64_e32 v[46:47], v[14:15]
	v_mov_b64_e32 v[62:63], v[14:15]
	v_mov_b64_e32 v[28:29], v[12:13]
	v_mov_b64_e32 v[26:27], v[10:11]
	v_mov_b64_e32 v[24:25], v[8:9]
	v_mov_b64_e32 v[22:23], v[6:7]
	v_mov_b64_e32 v[20:21], v[4:5]
	v_mov_b64_e32 v[18:19], v[2:3]
	v_mov_b64_e32 v[16:17], v[0:1]
	v_mov_b64_e32 v[44:45], v[12:13]
	v_mov_b64_e32 v[42:43], v[10:11]
	v_mov_b64_e32 v[40:41], v[8:9]
	v_mov_b64_e32 v[38:39], v[6:7]
	v_mov_b64_e32 v[36:37], v[4:5]
	v_mov_b64_e32 v[34:35], v[2:3]
	v_mov_b64_e32 v[32:33], v[0:1]
	v_mov_b64_e32 v[60:61], v[12:13]
	v_mov_b64_e32 v[58:59], v[10:11]
	v_mov_b64_e32 v[56:57], v[8:9]
	v_mov_b64_e32 v[54:55], v[6:7]
	v_mov_b64_e32 v[52:53], v[4:5]
	v_mov_b64_e32 v[50:51], v[2:3]
	v_mov_b64_e32 v[48:49], v[0:1]
	s_waitcnt lgkmcnt(0)
	s_barrier
